# v18_hysk
# speedup vs baseline: 1.0250x; 1.0054x over previous
; __device__ __forceinline__ void p4_mix(const Params& p, int layer, char* shm) {
;   const int nAf = 256, nDf = 512, nH = 1024, nAs = 32, nDs = 64, nP = 4 * 43;
;   const int total = nAf + nDf + nH + nAs + nDs + nP;
;   unsigned* qhead = (unsigned*)(p.ws + O_QH) + layer * 16;
;   volatile unsigned* qslot = (volatile unsigned*)(shm + 131056);
;   int it = blockIdx.x;
;   for (;;) {
;     if (it >= nAf + nDf) {
;       __syncthreads();
;       if (threadIdx.x == 0) *qslot = __hip_atomic_fetch_add(qhead, 1u, __ATOMIC_RELAXED, __HIP_MEMORY_SCOPE_AGENT);
;       __syncthreads();
;       it = nAf + nDf + (int)*qslot;
;     }
;     if (it >= total) break;
;     int i = it;
;     it += gridDim.x;
;     int kind, qt = 0, hid = 0;
.LBB0_441:
	s_or_b64 exec, exec, s[0:1]
	s_mov_b32 s98, 0
	s_lshl_b32 s54, s68, 4
	s_lshl_b64 s[0:1], s[54:55], 2
	v_readlane_b32 s4, v254, 20
	s_add_u32 s4, s4, s0
	v_readlane_b32 s0, v254, 21
	s_addc_u32 s5, s0, s1
	v_writelane_b32 v255, s4, 5
	s_lshl_b32 s0, s68, 2
	s_lshl_b32 s54, s68, 10
	v_writelane_b32 v255, s5, 6
	v_writelane_b32 v255, s0, 7
	s_lshl_b32 s0, s68, 11
	v_writelane_b32 v255, s0, 8
	s_bitset1_b32 s0, 10
	v_readlane_b32 s4, v253, 42
	v_writelane_b32 v255, s0, 9
	v_writelane_b32 v254, s54, 58
	s_lshl_b64 s[0:1], s[54:55], 2
	v_readlane_b32 s8, v253, 46
	v_readlane_b32 s9, v253, 47
	s_add_u32 s0, s8, s0
	s_addc_u32 s1, s9, s1
	v_writelane_b32 v254, s55, 59
	v_writelane_b32 v255, s0, 10
	s_mov_b64 s[46:47], 0
	s_nop 0
	v_writelane_b32 v255, s1, 11
	v_readlane_b32 s0, v254, 51
	s_barrier
	s_nop 0
	v_mov_b32_e32 v137, s0
	v_readlane_b32 s5, v253, 43
	v_readlane_b32 s6, v253, 44
	v_readlane_b32 s7, v253, 45
	v_readlane_b32 s10, v253, 48
	v_readlane_b32 s11, v253, 49
	v_readlane_b32 s12, v253, 50
	v_readlane_b32 s13, v253, 51
	v_readlane_b32 s14, v253, 52
	v_readlane_b32 s15, v253, 53
	v_readlane_b32 s16, v253, 54
	v_readlane_b32 s17, v253, 55
	v_readlane_b32 s18, v253, 56
	v_readlane_b32 s19, v253, 57
	s_branch .LBB0_445

; __device__ __forceinline__ void p4_mix(const Params& p, int layer, char* shm) {
;     ...
;   for (;;) {
;     if (it >= nAf + nDf) {
;       __syncthreads();
;       if (threadIdx.x == 0) *qslot = __hip_atomic_fetch_add(qhead, 1u, __ATOMIC_RELAXED, __HIP_MEMORY_SCOPE_AGENT);
;       __syncthreads();
;       it = nAf + nDf + (int)*qslot;
;     }
.LBB0_445:
	s_movk_i32 s0, 0x2ff
	v_cmp_lt_i32_e32 vcc, s0, v137
	s_and_saveexec_b64 s[0:1], vcc
	s_cbranch_execz .LBB0_451
	s_barrier
	s_mov_b64 s[6:7], exec
	v_readlane_b32 s4, v253, 5
	v_readlane_b32 s5, v253, 6
	s_and_b64 s[4:5], s[6:7], s[4:5]
	s_mov_b64 exec, s[4:5]
	s_cbranch_execz .LBB0_450
	s_mov_b64 s[8:9], exec
	s_waitcnt vmcnt(0)
	v_mbcnt_lo_u32_b32 v0, s8, 0
	v_mbcnt_hi_u32_b32 v0, s9, v0
	v_cmp_eq_u32_e32 vcc, 0, v0
	s_and_saveexec_b64 s[4:5], vcc
	s_cbranch_execz .LBB0_449
	s_bcnt1_i32_b64 s8, s[8:9]
	v_mov_b32_e32 v2, s8
	v_mov_b32_e32 v251, s8
	v_readlane_b32 s8, v255, 5
	v_readlane_b32 s9, v255, 6
	s_nop 4
	s_cmp_lg_u32 s98, 0
	s_cbranch_scc1 .Lmy_q_have
	global_atomic_add v2, v1, v2, s[8:9] sc0
	s_waitcnt vmcnt(0)
	s_branch .Lmy_q_pref
.Lmy_q_have:
	v_mov_b32_e32 v2, v250
.Lmy_q_pref:
	s_mov_b32 s98, 1
	s_nop 0
	global_atomic_add v250, v1, v251, s[8:9] sc0
.LBB0_449:
	s_or_b64 exec, exec, s[4:5]
	s_mov_b64 s[4:5], src_shared_base
	s_nop 1
	v_readfirstlane_b32 s4, v2
	v_mov_b32_e32 v137, s5
	s_nop 0
	v_add_u32_e32 v0, s4, v0
	ds_write_b32 v136, v0
.LBB0_450:
	s_or_b64 exec, exec, s[6:7]
	s_mov_b64 s[4:5], src_shared_base
	v_mov_b32_e32 v137, s5
	s_waitcnt lgkmcnt(0)
	s_barrier
	ds_read_b32 v0, v136
	s_waitcnt lgkmcnt(0)
	v_add_u32_e32 v137, 0x300, v0

; __device__ __forceinline__ void hyena_item(const Params& p, int layer, int c, bf16_t* sm) {
;     ...
;   const int s0c = (8 - (l15 & 7)) & 7;
;   const char* abase = smc + hy_copy_base(s0c) + (GTC - l15 + 8 * quad - s0c) * 2;
;   const bf16_t* zfrag = zb + (l15 & 3) * ZS + ZM + 16 * (l15 >> 2) + 8 * quad;
;   const int ob = l15 & 3, ot = 16 * (l15 >> 2) + quad * 4;
;     ...
;     const float sk = p.b_skip[(layer * 2 + o) * 1024 + c];
.LBB0_543:
	s_or_b64 exec, exec, s[0:1]
	v_sub_u32_e32 v0, 0, v114
	v_and_b32_e32 v0, 7, v0
	v_and_b32_e32 v14, 15, v114
	v_cmp_ne_u32_e32 vcc, 0, v0
	v_add_u32_e32 v21, v0, v14
	v_mul_u32_u24_e32 v15, 0x2200, v0
	v_lshlrev_b32_e32 v2, 2, v0
	v_mov_b32_e32 v20, 0xeda87430
	v_lshrrev_b32_e32 v20, v2, v20
	v_and_b32_e32 v20, 15, v20
	v_lshlrev_b32_e32 v20, 4, v20
	v_lshlrev_b32_e32 v2, 3, v13
	v_sub_u32_e32 v0, v2, v21
	v_lshlrev_b32_e32 v0, 1, v0
	v_add3_u32 v186, v20, v15, v0
	v_lshlrev_b32_e32 v0, 3, v114
	v_mul_u32_u24_e32 v128, 0x11a0, v12
	v_and_b32_e32 v0, 0x60, v0
	v_lshlrev_b32_e32 v13, 4, v13
	v_add3_u32 v187, v128, v0, v13
	v_not_b32_e32 v0, v114
	v_lshlrev_b32_e32 v0, 1, v0
	v_and_b32_e32 v0, 0xffffff80, v0
	v_add_u32_e32 v188, v186, v0
	s_waitcnt lgkmcnt(0)
	s_barrier
	ds_read_b128 v[40:43], v188 offset:22720
	ds_read_b128 v[36:39], v188 offset:21696
	ds_read_b128 v[28:31], v188 offset:20672
	ds_read_b128 v[24:27], v187 offset:64
	ds_read_b128 v[32:35], v188 offset:19648
	v_mov_b32_e32 v2, v1
	v_mov_b32_e32 v3, v1
	v_mov_b32_e32 v0, v1
	v_mov_b64_e32 v[18:19], v[2:3]
	v_cmp_gt_u32_e32 vcc, 64, v114
	v_mov_b64_e32 v[16:17], v[0:1]
	s_and_saveexec_b64 s[0:1], vcc
	ds_read_b128 v[16:19], v186 offset:18496
	s_or_b64 exec, exec, s[0:1]
	v_mul_u32_u24_e32 v115, 0x810, v12
	v_add3_u32 v12, v20, v15, v13
	v_lshlrev_b32_e32 v15, 1, v21
	v_sub_u32_e32 v12, v12, v15
	v_add_u32_e32 v129, 0x4880, v12
	v_lshlrev_b32_e32 v12, 3, v14
	v_and_b32_e32 v12, 0x60, v12
	v_add_u32_e32 v12, v128, v12
	s_movk_i32 s0, 0x80
	v_add3_u32 v130, v12, v13, s0
	v_lshlrev_b32_e32 v12, 1, v114
	v_and_b32_e32 v12, 0xffffff80, v12
	v_mov_b32_e32 v44, 0
	v_mov_b64_e32 v[22:23], v[2:3]
	v_ashrrev_i32_e32 v117, 31, v116
	v_readlane_b32 s100, v253, 37
	v_readlane_b32 s101, v253, 38
	s_nop 4
	v_lshl_add_u64 v[248:249], v[116:117], 2, s[100:101]
	s_movk_i32 s100, 0x1000
	s_mov_b32 s101, 0
	global_load_dword v252, v[248:249], off
	v_lshl_add_u64 v[246:247], v[248:249], 0, s[100:101]
	s_nop 0
	global_load_dword v245, v[246:247], off
	v_sub_u32_e32 v131, 0, v12
	s_mov_b32 s4, -2
	v_mov_b32_e32 v107, v130
	v_mov_b32_e32 v109, v129
	v_mov_b64_e32 v[20:21], v[0:1]
	v_mov_b32_e32 v45, v44
	v_mov_b32_e32 v46, v44
	v_mov_b32_e32 v47, v44
	v_mov_b32_e32 v56, v44
	v_mov_b32_e32 v57, v44
	v_mov_b32_e32 v58, v44
	v_mov_b32_e32 v59, v44
	v_mov_b32_e32 v52, v44
	v_mov_b32_e32 v53, v44
	v_mov_b32_e32 v54, v44
	v_mov_b32_e32 v55, v44
	v_mov_b32_e32 v48, v44
	v_mov_b32_e32 v49, v44
	v_mov_b32_e32 v50, v44
	v_mov_b32_e32 v51, v44
	v_mov_b32_e32 v12, v44
	v_mov_b32_e32 v13, v44
	v_mov_b32_e32 v14, v44
	v_mov_b32_e32 v15, v44
	s_branch .LBB0_547

; __device__ __forceinline__ float bflo(unsigned w) { return __uint_as_float(w << 16); }
; __device__ __forceinline__ float bfhi(unsigned w) { return __uint_as_float(w & 0xffff0000u); }
; #define HY_MMA(AF, BF) do { \
;       _Pragma("unroll") for (int tt = 0; tt < 4; ++tt) acc[tt] = mfma16(AF[tt], BF, acc[tt]); \
;       if (has5) acc[4] = mfma16(AF[4], BF, acc[4]); } while (0)
; __device__ __forceinline__ void hyena_item(const Params& p, int layer, int c, bf16_t* sm) {
;     ...
;     HY_MMA(a0, b0);
;     ...
;     __syncthreads();
;     const float sk = p.b_skip[(layer * 2 + o) * 1024 + c];
; #pragma unroll
;     for (int tt = 0; tt < 5; ++tt) {
;       const int Tt = wave + 8 * tt;
;       if (Tt <= 32) {
;         int t = 64 * Tt + ot;
;         if (t < L) {
;           u32x2 zw = *(const u32x2*)(zb + ob * ZS + ZM + t);
;           float v0 = bflo(gw[tt].x) * (acc[tt][0] + sk * bflo(zw.x));
;           float v1 = bfhi(gw[tt].x) * (acc[tt][1] + sk * bfhi(zw.x));
;           float v2 = bflo(gw[tt].y) * (acc[tt][2] + sk * bflo(zw.y));
;           float v3 = bfhi(gw[tt].y) * (acc[tt][3] + sk * bfhi(zw.y));
.LBB0_555:
	s_waitcnt lgkmcnt(3)
	v_mfma_f32_16x16x32_bf16 v[40:43], v[40:43], v[24:27], v[44:47]
	s_waitcnt lgkmcnt(2)
	v_mfma_f32_16x16x32_bf16 v[36:39], v[36:39], v[24:27], v[56:59]
	s_waitcnt lgkmcnt(1)
	v_mfma_f32_16x16x32_bf16 v[28:31], v[28:31], v[24:27], v[52:55]
	s_waitcnt lgkmcnt(0)
	v_mfma_f32_16x16x32_bf16 v[20:23], v[32:35], v[24:27], v[48:51]
	s_and_saveexec_b64 s[0:1], vcc
	v_mfma_f32_16x16x32_bf16 v[12:15], v[16:19], v[24:27], v[12:15]
	s_or_b64 exec, exec, s[0:1]
	v_readlane_b32 s72, v253, 23
	v_readlane_b32 s86, v253, 37
	v_readlane_b32 s87, v253, 38
	s_barrier
	s_nop 0
	v_lshl_add_u64 v[70:71], v[116:117], 2, s[86:87]
	s_waitcnt vmcnt(0)
	v_mov_b32_e32 v0, v252
	v_and_or_b32 v185, v114, s90, v179
	v_readlane_b32 s73, v253, 24
	v_readlane_b32 s74, v253, 25
	v_readlane_b32 s75, v253, 26
	v_readlane_b32 s76, v253, 27
	v_readlane_b32 s77, v253, 28
	v_readlane_b32 s78, v253, 29
	v_readlane_b32 s79, v253, 30
	v_readlane_b32 s80, v253, 31
	v_readlane_b32 s81, v253, 32
	v_readlane_b32 s82, v253, 33
	v_readlane_b32 s83, v253, 34
	v_readlane_b32 s84, v253, 35
	v_readlane_b32 s85, v253, 36
	s_and_saveexec_b64 s[30:31], s[14:15]
	s_cbranch_execz .LBB0_560
	v_cmp_gt_i32_e64 s[0:1], s69, v185
	s_and_b64 exec, exec, s[0:1]
	s_cbranch_execz .LBB0_560
	v_lshl_add_u32 v16, v185, 1, v128
	ds_read_b64 v[2:3], v16 offset:192
	s_waitcnt lgkmcnt(0)
	v_and_b32_e32 v17, 0xffff0000, v3
	v_lshlrev_b32_e32 v3, 16, v3
	v_and_b32_e32 v18, 0xffff0000, v2
	v_lshlrev_b32_e32 v2, 16, v2
	s_waitcnt vmcnt(0)
	v_fmac_f32_e32 v42, v0, v3
	v_lshlrev_b32_e32 v3, 16, v127
	v_fmac_f32_e32 v40, v0, v2
	v_lshlrev_b32_e32 v2, 16, v126
	v_fmac_f32_e32 v43, v0, v17
	v_and_b32_e32 v17, 0xffff0000, v127
	v_mul_f32_e32 v3, v42, v3
	v_fmac_f32_e32 v41, v0, v18
	v_and_b32_e32 v18, 0xffff0000, v126
	v_mul_f32_e32 v2, v40, v2
	v_mul_f32_e32 v17, v43, v17
	v_mul_f32_e32 v18, v41, v18
	v_cvt_pk_bf16_f32 v2, v2, v18
	v_cvt_pk_bf16_f32 v3, v3, v17
	ds_write_b64 v16, v[2:3] offset:192

; __device__ __forceinline__ float bflo(unsigned w) { return __uint_as_float(w << 16); }
; __device__ __forceinline__ float bfhi(unsigned w) { return __uint_as_float(w & 0xffff0000u); }
; #define HY_MMA(AF, BF) do { \
;       _Pragma("unroll") for (int tt = 0; tt < 4; ++tt) acc[tt] = mfma16(AF[tt], BF, acc[tt]); \
;       if (has5) acc[4] = mfma16(AF[4], BF, acc[4]); } while (0)
; __device__ __forceinline__ void hyena_item(const Params& p, int layer, int c, bf16_t* sm) {
;     ...
;     HY_MMA(a0, b0);
;     ...
;     __syncthreads();
;     const float sk = p.b_skip[(layer * 2 + o) * 1024 + c];
; #pragma unroll
;     for (int tt = 0; tt < 5; ++tt) {
;       const int Tt = wave + 8 * tt;
;       if (Tt <= 32) {
;         int t = 64 * Tt + ot;
;         if (t < L) {
;           u32x2 zw = *(const u32x2*)(zb + ob * ZS + ZM + t);
;           float v0 = bflo(gw[tt].x) * (acc[tt][0] + sk * bflo(zw.x));
;           float v1 = bfhi(gw[tt].x) * (acc[tt][1] + sk * bfhi(zw.x));
;           float v2 = bflo(gw[tt].y) * (acc[tt][2] + sk * bflo(zw.y));
;           float v3 = bfhi(gw[tt].y) * (acc[tt][3] + sk * bfhi(zw.y));
;           if (o == 0) {
;             u32x2 nz = {pack2(v0, v1), pack2(v2, v3)};
;             *(u32x2*)(zb + ob * ZS + ZM + t) = nz;
;           } else {
;             bf16_t* yb = WSH(YB) + (size_t)(ob * L + t) * 1024 + c;
;             const unsigned y01 = pack2(v0, v1), y23 = pack2(v2, v3);
;             yb[0] = (bf16_t)(y01 & 0xffffu); yb[1024] = (bf16_t)(y01 >> 16); yb[2048] = (bf16_t)(y23 & 0xffffu); yb[3072] = (bf16_t)(y23 >> 16);
;           }
.LBB0_619:
	s_waitcnt lgkmcnt(3)
	v_mfma_f32_16x16x32_bf16 v[30:33], v[30:33], v[14:17], v[34:37]
	s_waitcnt lgkmcnt(2)
	v_mfma_f32_16x16x32_bf16 v[26:29], v[26:29], v[14:17], v[46:49]
	s_waitcnt lgkmcnt(1)
	v_mfma_f32_16x16x32_bf16 v[18:21], v[18:21], v[14:17], v[42:45]
	s_waitcnt lgkmcnt(0)
	v_mfma_f32_16x16x32_bf16 v[6:9], v[22:25], v[14:17], v[38:41]
	s_and_saveexec_b64 s[0:1], vcc
	v_mfma_f32_16x16x32_bf16 v[2:5], v[10:13], v[14:17], v[2:5]
	s_or_b64 exec, exec, s[0:1]
	v_add_co_u32_e32 v10, vcc, 0x1000, v70
	s_nop 1
	v_addc_co_u32_e32 v11, vcc, 0, v71, vcc
	s_barrier
	s_waitcnt vmcnt(0)
	v_mov_b32_e32 v0, v245
	v_ashrrev_i32_e32 v81, 31, v80
	s_and_saveexec_b64 s[0:1], s[14:15]
	s_cbranch_execz .LBB0_624
	v_cmp_gt_i32_e32 vcc, s69, v185
	s_and_b64 exec, exec, vcc
	s_cbranch_execz .LBB0_624
	v_lshl_add_u32 v10, v185, 1, v128
	ds_read_b64 v[10:11], v10 offset:192
	v_readlane_b32 s4, v254, 26
	v_readlane_b32 s5, v254, 27
	s_waitcnt lgkmcnt(0)
	v_and_b32_e32 v12, 0xffff0000, v11
	v_lshlrev_b32_e32 v11, 16, v11
	s_waitcnt vmcnt(0)
	v_fmac_f32_e32 v32, v0, v11
	v_lshlrev_b32_e32 v11, 16, v83
	v_mul_f32_e32 v13, v32, v11
	v_and_b32_e32 v11, 0xffff0000, v10
	v_lshlrev_b32_e32 v10, 16, v10
	v_fmac_f32_e32 v30, v0, v10
	v_lshlrev_b32_e32 v10, 16, v82
	v_fmac_f32_e32 v31, v0, v11
	v_and_b32_e32 v11, 0xffff0000, v82
	v_mul_f32_e32 v15, v30, v10
	v_add_u32_e32 v10, v185, v115
	v_mul_f32_e32 v14, v31, v11
	v_ashrrev_i32_e32 v11, 31, v10
	v_lshlrev_b64 v[10:11], 11, v[10:11]
	v_fmac_f32_e32 v33, v0, v12
	v_and_b32_e32 v12, 0xffff0000, v83
	v_lshl_add_u64 v[10:11], s[4:5], 0, v[10:11]
	v_mul_f32_e32 v12, v33, v12
	v_lshl_add_u64 v[10:11], v[80:81], 1, v[10:11]
	v_cvt_pk_bf16_f32 v14, v15, v14
	v_cvt_pk_bf16_f32 v12, v13, v12
	global_store_short v[10:11], v14, off
	global_store_short_d16_hi v[10:11], v14, off offset:2048
	v_add_co_u32_e32 v10, vcc, 0x1000, v10
	s_nop 1
	v_addc_co_u32_e32 v11, vcc, 0, v11, vcc
	global_store_short v[10:11], v12, off
	global_store_short_d16_hi v[10:11], v12, off offset:2048

; __global__ void __launch_bounds__(512, 2) mega(Params p) {
;   __shared__ __attribute__((aligned(1024))) char smem[2 * (256 + 256) * 64 * 2];
	.amdhsa_kernel _Z4mega6Params
		.amdhsa_group_segment_fixed_size 131072
		.amdhsa_private_segment_fixed_size 0
		.amdhsa_kernarg_size 456
		.amdhsa_user_sgpr_count 2
		.amdhsa_user_sgpr_dispatch_ptr 0
		.amdhsa_user_sgpr_queue_ptr 0
		.amdhsa_user_sgpr_kernarg_segment_ptr 1
		.amdhsa_user_sgpr_dispatch_id 0
		.amdhsa_user_sgpr_kernarg_preload_length 0
		.amdhsa_user_sgpr_kernarg_preload_offset 0
		.amdhsa_user_sgpr_private_segment_size 0
		.amdhsa_uses_dynamic_stack 0
		.amdhsa_enable_private_segment 0
		.amdhsa_system_sgpr_workgroup_id_x 1
		.amdhsa_system_sgpr_workgroup_id_y 0
		.amdhsa_system_sgpr_workgroup_id_z 0
		.amdhsa_system_sgpr_workgroup_info 0
		.amdhsa_system_vgpr_workitem_id 2
		.amdhsa_next_free_vgpr 256
		.amdhsa_next_free_sgpr 102
		.amdhsa_accum_offset 256
		.amdhsa_reserve_vcc 1
		.amdhsa_float_round_mode_32 0
		.amdhsa_float_round_mode_16_64 0
		.amdhsa_float_denorm_mode_32 3
		.amdhsa_float_denorm_mode_16_64 3
		.amdhsa_dx10_clamp 1
		.amdhsa_ieee_mode 1
		.amdhsa_fp16_overflow 0
		.amdhsa_tg_split 0
		.amdhsa_exception_fp_ieee_invalid_op 0
		.amdhsa_exception_fp_denorm_src 0
		.amdhsa_exception_fp_ieee_div_zero 0
		.amdhsa_exception_fp_ieee_overflow 0
		.amdhsa_exception_fp_ieee_underflow 0
		.amdhsa_exception_fp_ieee_inexact 0
		.amdhsa_exception_int_div_zero 0
	.end_amdhsa_kernel

; __global__ void __launch_bounds__(512, 2) mega(Params p) {
;   __shared__ __attribute__((aligned(1024))) char smem[2 * (256 + 256) * 64 * 2];
amdhsa.kernels:
  - .agpr_count:     0
    .args:
      - .offset:         0
        .size:           200
        .value_kind:     by_value
      - .offset:         200
        .size:           4
        .value_kind:     hidden_block_count_x
      - .offset:         204
        .size:           4
        .value_kind:     hidden_block_count_y
      - .offset:         208
        .size:           4
        .value_kind:     hidden_block_count_z
      - .offset:         212
        .size:           2
        .value_kind:     hidden_group_size_x
      - .offset:         214
        .size:           2
        .value_kind:     hidden_group_size_y
      - .offset:         216
        .size:           2
        .value_kind:     hidden_group_size_z
      - .offset:         218
        .size:           2
        .value_kind:     hidden_remainder_x
      - .offset:         220
        .size:           2
        .value_kind:     hidden_remainder_y
      - .offset:         222
        .size:           2
        .value_kind:     hidden_remainder_z
      - .offset:         240
        .size:           8
        .value_kind:     hidden_global_offset_x
      - .offset:         248
        .size:           8
        .value_kind:     hidden_global_offset_y
      - .offset:         256
        .size:           8
        .value_kind:     hidden_global_offset_z
      - .offset:         264
        .size:           2
        .value_kind:     hidden_grid_dims
      - .offset:         288
        .size:           8
        .value_kind:     hidden_multigrid_sync_arg
    .group_segment_fixed_size: 131072
    .kernarg_segment_align: 8
    .kernarg_segment_size: 456
    .language:       OpenCL C
    .language_version:
      - 2
      - 0
    .max_flat_workgroup_size: 512
    .name:           _Z4mega6Params
    .private_segment_fixed_size: 0
    .sgpr_count:     108
    .sgpr_spill_count: 168
    .symbol:         _Z4mega6Params.kd
    .uniform_work_group_size: 1
    .uses_dynamic_stack: false
    .vgpr_count:     256
    .vgpr_spill_count: 0
    .wavefront_size: 64
